# grid-barrier wait: four staggered polls in flight instead of three
# baseline (speedup 1.0000x reference)
; __device__ __forceinline__ unsigned xb_ld(unsigned* p)              { return __hip_atomic_load(p, __ATOMIC_RELAXED, __HIP_MEMORY_SCOPE_AGENT); }
; #define XB_SPIN(cond, bar) do { unsigned _sp = 0; while (cond) { __builtin_amdgcn_s_sleep(1); \
;     if ((++_sp & 255u) == 0u) { if (xb_ld(&(bar)[XB_TMO])) break; if (_sp > XB_SPIN_CAP) { atomicAdd(&(bar)[XB_TMO], 1u); break; } } } } while (0)
; __device__ __forceinline__ void xcd_barrier(const XcdBarrier& b) {
;     ...
;         XB_SPIN(xb_ld(&bar[XB_XGEN(bx_)]) < (gen + 1u) * nx, bar);
;         __builtin_amdgcn_fence(__ATOMIC_ACQUIRE, "agent");
;         asm volatile("s_waitcnt vmcnt(0)" ::: "memory");
.LBB0_730:
	s_or_b64 exec, exec, s[0:1]
	s_add_i32 s84, s4, 0x900
	s_lshl_b64 s[0:1], s[84:85], 2
	s_add_u32 s0, s34, s0
	s_addc_u32 s1, s35, s1
	v_mul_lo_u32 v2, v5, v2
	v_mov_b64_e32 v[4:5], s[0:1]
	s_movk_i32 s2, 0x1000
	global_load_dword v6, v[4:5], off sc1
	s_sleep 10
	global_load_dword v7, v[4:5], off sc1
	s_sleep 10
	global_load_dword v8, v[4:5], off sc1
	s_sleep 10
	global_load_dword v9, v[4:5], off sc1
.Lpp0_loop:
	s_waitcnt vmcnt(3)
	v_cmp_ge_u32_e32 vcc, v6, v2
	s_cbranch_vccnz .Lpp0_hit
	global_load_dword v6, v[4:5], off sc1
	s_waitcnt vmcnt(3)
	v_cmp_ge_u32_e32 vcc, v7, v2
	s_cbranch_vccnz .Lpp0_hit
	global_load_dword v7, v[4:5], off sc1
	s_waitcnt vmcnt(3)
	v_cmp_ge_u32_e32 vcc, v8, v2
	s_cbranch_vccnz .Lpp0_hit
	global_load_dword v8, v[4:5], off sc1
	s_waitcnt vmcnt(3)
	v_cmp_ge_u32_e32 vcc, v9, v2
	s_cbranch_vccnz .Lpp0_hit
	global_load_dword v9, v[4:5], off sc1
	s_sub_u32 s2, s2, 1
	s_cmp_lg_u32 s2, 0
	s_cbranch_scc1 .Lpp0_loop
	s_branch .Lpp0_miss
